# T9 + odd-layer LN epilogue pipelining + sort-stage gathers merged + EpiOddIn rope table loads hoisted into a pre-pass
# speedup vs baseline: 1.0150x; 1.0145x over previous
; #define GAS __attribute__((address_space(1)))
; __device__ __forceinline__ bf16_t f2bf(float f) { return (bf16_t)(cvtpk(f, 0.f) & 0xffffu); }
;     __device__ __forceinline__ void operator()(const f32x4 (&acc)[2][2][4][2], int brow, int bcol, int wr, int wc, int fr, int fq) const {
;     ...
;         } else if (bcol < 3072) {
;             const int g2 = (bcol - 1024) >> 10, vh0 = ((bcol - 1024) & 1023) >> 7, i = wc * 16 + fr;
;             bf16_t* dst = att + 2 * MHSZ + EHSZ + (size_t)g2 * EHSZ;
; #pragma unroll
;             for (int ai = 0; ai < 2; ++ai)
; #pragma unroll
;                 for (int m = 0; m < 4; ++m)
; #pragma unroll
;                     for (int j = 0; j < 4; ++j) {
;                         const int sq = (brow & 4095) + ai * 128 + wr * 64 + m * 16 + fq * 4 + j;
;                         const float2 cs = r128[sq * 64 + i];
; #pragma unroll
;                         for (int bj = 0; bj < 2; ++bj) {
;                             const float x1 = acc[ai][bj][m][0][j], x2 = acc[ai][bj][m][1][j];
;                             GAS bf16_t* p = (GAS bf16_t*)(dst + ((size_t)(b * 8 + vh0 + bj) * S + sq) * 128);
;                             p[i] = f2bf(x1 * cs.x - x2 * cs.y); p[64 + i] = f2bf(x2 * cs.x + x1 * cs.y);
;                         }
;                     }
.LBB0_616:
	s_andn2_b64 vcc, exec, s[12:13]
	s_cbranch_vccnz .LBB0_618
	s_add_i32 s12, s50, 0xfffffc00
	s_lshr_b32 s13, s78, 7
	s_lshr_b32 s12, s12, 10
	s_and_b32 s17, s13, 6
	s_mov_b32 s13, s86
	s_lshl_b64 s[12:13], s[12:13], 24
	s_add_u32 s52, s79, s12
	s_addc_u32 s53, s87, s13
	s_and_b32 s12, s40, 0xf00
	v_add_u32_e32 v2, s12, v136
	v_lshl_or_b32 v137, v1, 4, v135
	v_lshl_or_b32 v132, v134, 2, v2
	v_mov_b32_e32 v242, v132
	v_lshl_or_b32 v240, v242, 6, v137
	v_ashrrev_i32_e32 v241, 31, v240
	v_lshl_add_u64 v[240:241], v[240:241], 3, s[48:49]
	global_load_dwordx2 v[144:145], v[240:241], off
	v_or_b32_e32 v242, 1, v132
	v_lshl_or_b32 v240, v242, 6, v137
	v_ashrrev_i32_e32 v241, 31, v240
	v_lshl_add_u64 v[240:241], v[240:241], 3, s[48:49]
	global_load_dwordx2 v[146:147], v[240:241], off
	v_or_b32_e32 v242, 2, v132
	v_lshl_or_b32 v240, v242, 6, v137
	v_ashrrev_i32_e32 v241, 31, v240
	v_lshl_add_u64 v[240:241], v[240:241], 3, s[48:49]
	global_load_dwordx2 v[148:149], v[240:241], off
	v_or_b32_e32 v242, 3, v132
	v_lshl_or_b32 v240, v242, 6, v137
	v_ashrrev_i32_e32 v241, 31, v240
	v_lshl_add_u64 v[240:241], v[240:241], 3, s[48:49]
	global_load_dwordx2 v[150:151], v[240:241], off
	v_or_b32_e32 v242, 16, v132
	v_lshl_or_b32 v240, v242, 6, v137
	v_ashrrev_i32_e32 v241, 31, v240
	v_lshl_add_u64 v[240:241], v[240:241], 3, s[48:49]
	global_load_dwordx2 v[152:153], v[240:241], off
	v_or_b32_e32 v242, 17, v132
	v_lshl_or_b32 v240, v242, 6, v137
	v_ashrrev_i32_e32 v241, 31, v240
	v_lshl_add_u64 v[240:241], v[240:241], 3, s[48:49]
	global_load_dwordx2 v[154:155], v[240:241], off
	v_or_b32_e32 v242, 18, v132
	v_lshl_or_b32 v240, v242, 6, v137
	v_ashrrev_i32_e32 v241, 31, v240
	v_lshl_add_u64 v[240:241], v[240:241], 3, s[48:49]
	global_load_dwordx2 v[156:157], v[240:241], off
	v_or_b32_e32 v242, 19, v132
	v_lshl_or_b32 v240, v242, 6, v137
	v_ashrrev_i32_e32 v241, 31, v240
	v_lshl_add_u64 v[240:241], v[240:241], 3, s[48:49]
	global_load_dwordx2 v[158:159], v[240:241], off
	v_or_b32_e32 v242, 32, v132
	v_lshl_or_b32 v240, v242, 6, v137
	v_ashrrev_i32_e32 v241, 31, v240
	v_lshl_add_u64 v[240:241], v[240:241], 3, s[48:49]
	global_load_dwordx2 v[160:161], v[240:241], off
	v_or_b32_e32 v242, 33, v132
	v_lshl_or_b32 v240, v242, 6, v137
	v_ashrrev_i32_e32 v241, 31, v240
	v_lshl_add_u64 v[240:241], v[240:241], 3, s[48:49]
	global_load_dwordx2 v[162:163], v[240:241], off
	v_or_b32_e32 v242, 34, v132
	v_lshl_or_b32 v240, v242, 6, v137
	v_ashrrev_i32_e32 v241, 31, v240
	v_lshl_add_u64 v[240:241], v[240:241], 3, s[48:49]
	global_load_dwordx2 v[164:165], v[240:241], off
	v_or_b32_e32 v242, 35, v132
	v_lshl_or_b32 v240, v242, 6, v137
	v_ashrrev_i32_e32 v241, 31, v240
	v_lshl_add_u64 v[240:241], v[240:241], 3, s[48:49]
	global_load_dwordx2 v[166:167], v[240:241], off
	v_or_b32_e32 v242, 48, v132
	v_lshl_or_b32 v240, v242, 6, v137
	v_ashrrev_i32_e32 v241, 31, v240
	v_lshl_add_u64 v[240:241], v[240:241], 3, s[48:49]
	global_load_dwordx2 v[168:169], v[240:241], off
	v_or_b32_e32 v242, 49, v132
	v_lshl_or_b32 v240, v242, 6, v137
	v_ashrrev_i32_e32 v241, 31, v240
	v_lshl_add_u64 v[240:241], v[240:241], 3, s[48:49]
	global_load_dwordx2 v[170:171], v[240:241], off
	v_or_b32_e32 v242, 50, v132
	v_lshl_or_b32 v240, v242, 6, v137
	v_ashrrev_i32_e32 v241, 31, v240
	v_lshl_add_u64 v[240:241], v[240:241], 3, s[48:49]
	global_load_dwordx2 v[172:173], v[240:241], off
	v_or_b32_e32 v242, 51, v132
	v_lshl_or_b32 v240, v242, 6, v137
	v_ashrrev_i32_e32 v241, 31, v240
	v_lshl_add_u64 v[240:241], v[240:241], 3, s[48:49]
	global_load_dwordx2 v[174:175], v[240:241], off
	v_add_u32_e32 v242, 0x80, v132
	v_lshl_or_b32 v240, v242, 6, v137
	v_ashrrev_i32_e32 v241, 31, v240
	v_lshl_add_u64 v[240:241], v[240:241], 3, s[48:49]
	global_load_dwordx2 v[176:177], v[240:241], off
	v_add_u32_e32 v242, 0x81, v132
	v_lshl_or_b32 v240, v242, 6, v137
	v_ashrrev_i32_e32 v241, 31, v240
	v_lshl_add_u64 v[240:241], v[240:241], 3, s[48:49]
	global_load_dwordx2 v[178:179], v[240:241], off
	v_add_u32_e32 v242, 0x82, v132
	v_lshl_or_b32 v240, v242, 6, v137
	v_ashrrev_i32_e32 v241, 31, v240
	v_lshl_add_u64 v[240:241], v[240:241], 3, s[48:49]
	global_load_dwordx2 v[180:181], v[240:241], off
	v_add_u32_e32 v242, 0x83, v132
	v_lshl_or_b32 v240, v242, 6, v137
	v_ashrrev_i32_e32 v241, 31, v240
	v_lshl_add_u64 v[240:241], v[240:241], 3, s[48:49]
	global_load_dwordx2 v[182:183], v[240:241], off
	v_add_u32_e32 v242, 0x90, v132
	v_lshl_or_b32 v240, v242, 6, v137
	v_ashrrev_i32_e32 v241, 31, v240
	v_lshl_add_u64 v[240:241], v[240:241], 3, s[48:49]
	global_load_dwordx2 v[184:185], v[240:241], off
	v_add_u32_e32 v242, 0x91, v132
	v_lshl_or_b32 v240, v242, 6, v137
	v_ashrrev_i32_e32 v241, 31, v240
	v_lshl_add_u64 v[240:241], v[240:241], 3, s[48:49]
	global_load_dwordx2 v[186:187], v[240:241], off
	v_add_u32_e32 v242, 0x92, v132
	v_lshl_or_b32 v240, v242, 6, v137
	v_ashrrev_i32_e32 v241, 31, v240
	v_lshl_add_u64 v[240:241], v[240:241], 3, s[48:49]
	global_load_dwordx2 v[188:189], v[240:241], off
	v_add_u32_e32 v242, 0x93, v132
	v_lshl_or_b32 v240, v242, 6, v137
	v_ashrrev_i32_e32 v241, 31, v240
	v_lshl_add_u64 v[240:241], v[240:241], 3, s[48:49]
	global_load_dwordx2 v[190:191], v[240:241], off
	v_add_u32_e32 v242, 0xa0, v132
	v_lshl_or_b32 v240, v242, 6, v137
	v_ashrrev_i32_e32 v241, 31, v240
	v_lshl_add_u64 v[240:241], v[240:241], 3, s[48:49]
	global_load_dwordx2 v[192:193], v[240:241], off
	v_add_u32_e32 v242, 0xa1, v132
	v_lshl_or_b32 v240, v242, 6, v137
	v_ashrrev_i32_e32 v241, 31, v240
	v_lshl_add_u64 v[240:241], v[240:241], 3, s[48:49]
	global_load_dwordx2 v[194:195], v[240:241], off
	v_add_u32_e32 v242, 0xa2, v132
	v_lshl_or_b32 v240, v242, 6, v137
	v_ashrrev_i32_e32 v241, 31, v240
	v_lshl_add_u64 v[240:241], v[240:241], 3, s[48:49]
	global_load_dwordx2 v[196:197], v[240:241], off
	v_add_u32_e32 v242, 0xa3, v132
	v_lshl_or_b32 v240, v242, 6, v137
	v_ashrrev_i32_e32 v241, 31, v240
	v_lshl_add_u64 v[240:241], v[240:241], 3, s[48:49]
	global_load_dwordx2 v[208:209], v[240:241], off
	v_add_u32_e32 v242, 0xb0, v132
	v_lshl_or_b32 v240, v242, 6, v137
	v_ashrrev_i32_e32 v241, 31, v240
	v_lshl_add_u64 v[240:241], v[240:241], 3, s[48:49]
	global_load_dwordx2 v[210:211], v[240:241], off
	v_add_u32_e32 v242, 0xb1, v132
	v_lshl_or_b32 v240, v242, 6, v137
	v_ashrrev_i32_e32 v241, 31, v240
	v_lshl_add_u64 v[240:241], v[240:241], 3, s[48:49]
	global_load_dwordx2 v[212:213], v[240:241], off
	v_add_u32_e32 v242, 0xb2, v132
	v_lshl_or_b32 v240, v242, 6, v137
	v_ashrrev_i32_e32 v241, 31, v240
	v_lshl_add_u64 v[240:241], v[240:241], 3, s[48:49]
	global_load_dwordx2 v[214:215], v[240:241], off
	v_add_u32_e32 v242, 0xb3, v132
	v_lshl_or_b32 v240, v242, 6, v137
	v_ashrrev_i32_e32 v241, 31, v240
	v_lshl_add_u64 v[240:241], v[240:241], 3, s[48:49]
	global_load_dwordx2 v[216:217], v[240:241], off
	s_waitcnt vmcnt(0)
; #define GAS __attribute__((address_space(1)))
; __device__ __forceinline__ bf16_t f2bf(float f) { return (bf16_t)(cvtpk(f, 0.f) & 0xffffu); }
;     __device__ __forceinline__ void operator()(const f32x4 (&acc)[2][2][4][2], int brow, int bcol, int wr, int wc, int fr, int fq) const {
;     ...
;                         const int sq = (brow & 4095) + ai * 128 + wr * 64 + m * 16 + fq * 4 + j;
;                         const float2 cs = r128[sq * 64 + i];
; #pragma unroll
;                         for (int bj = 0; bj < 2; ++bj) {
;                             const float x1 = acc[ai][bj][m][0][j], x2 = acc[ai][bj][m][1][j];
;                             GAS bf16_t* p = (GAS bf16_t*)(dst + ((size_t)(b * 8 + vh0 + bj) * S + sq) * 128);
;                             p[i] = f2bf(x1 * cs.x - x2 * cs.y); p[64 + i] = f2bf(x2 * cs.x + x1 * cs.y);
	s_lshl_b32 s12, s16, 3
	s_or_b32 s54, s12, s17
	v_ashrrev_i32_e32 v133, 31, v132
	v_lshlrev_b64 v[140:141], 8, v[132:133]
	s_ashr_i32 s55, s54, 31
	v_lshl_add_u64 v[140:141], s[52:53], 0, v[140:141]
	s_lshl_b64 s[56:57], s[54:55], 20
	v_lshl_add_u64 v[142:143], v[140:141], 0, s[56:57]
	s_or_b32 s12, s54, 1
	s_ashr_i32 s13, s12, 31
	s_lshl_b64 vcc, s[12:13], 20
	v_lshl_add_u64 v[140:141], v[140:141], 0, vcc
	v_mul_f32_e32 v2, v120, v145
	v_fma_f32 v2, v116, v144, -v2
	v_cvt_pk_bf16_f32 v133, v2, s0
	v_lshlrev_b32_e32 v2, 1, v137
	v_lshl_add_u64 v[142:143], v[142:143], 0, v[2:3]
	global_store_short v[142:143], v133, off
	v_mul_f32_e32 v133, v116, v145
	v_fmac_f32_e32 v133, v120, v144
	v_cvt_pk_bf16_f32 v133, v133, s0
	global_store_short v[142:143], v133, off offset:128
	v_mul_f32_e32 v133, v128, v145
	v_fma_f32 v133, v124, v144, -v133
	v_cvt_pk_bf16_f32 v133, v133, s0
	v_lshl_add_u64 v[140:141], v[140:141], 0, v[2:3]
	global_store_short v[140:141], v133, off
	v_mul_f32_e32 v133, v124, v145
	v_fmac_f32_e32 v133, v128, v144
	v_cvt_pk_bf16_f32 v133, v133, s0
	v_or_b32_e32 v138, 1, v132
	global_store_short v[140:141], v133, off offset:128
	v_ashrrev_i32_e32 v139, 31, v138
	v_lshlrev_b64 v[138:139], 8, v[138:139]
	v_lshl_add_u64 v[138:139], s[52:53], 0, v[138:139]
	v_lshl_add_u64 v[142:143], v[138:139], 0, s[56:57]
	v_lshl_add_u64 v[142:143], v[142:143], 0, v[2:3]
	v_lshl_add_u64 v[138:139], v[138:139], 0, vcc
	v_lshl_add_u64 v[138:139], v[138:139], 0, v[2:3]
	v_mul_f32_e32 v133, v121, v147
	v_fma_f32 v133, v117, v146, -v133
	v_cvt_pk_bf16_f32 v133, v133, s0
	global_store_short v[142:143], v133, off
	v_mul_f32_e32 v133, v117, v147
	v_fmac_f32_e32 v133, v121, v146
	v_cvt_pk_bf16_f32 v133, v133, s0
	global_store_short v[142:143], v133, off offset:128
	v_mul_f32_e32 v133, v129, v147
	v_fma_f32 v133, v125, v146, -v133
	v_cvt_pk_bf16_f32 v133, v133, s0
	global_store_short v[138:139], v133, off
	v_mul_f32_e32 v133, v125, v147
	v_fmac_f32_e32 v133, v129, v146
	v_cvt_pk_bf16_f32 v133, v133, s0
	global_store_short v[138:139], v133, off offset:128
	v_or_b32_e32 v138, 2, v132
	v_ashrrev_i32_e32 v139, 31, v138
	v_lshlrev_b64 v[138:139], 8, v[138:139]
	v_lshl_add_u64 v[138:139], s[52:53], 0, v[138:139]
	v_lshl_add_u64 v[142:143], v[138:139], 0, s[56:57]
	v_lshl_add_u64 v[142:143], v[142:143], 0, v[2:3]
	v_lshl_add_u64 v[138:139], v[138:139], 0, vcc
	v_lshl_add_u64 v[138:139], v[138:139], 0, v[2:3]
	v_mul_f32_e32 v133, v122, v149
	v_fma_f32 v133, v118, v148, -v133
	v_cvt_pk_bf16_f32 v133, v133, s0
	global_store_short v[142:143], v133, off
	v_mul_f32_e32 v133, v118, v149
	v_fmac_f32_e32 v133, v122, v148
	v_cvt_pk_bf16_f32 v133, v133, s0
	global_store_short v[142:143], v133, off offset:128
	v_mul_f32_e32 v133, v130, v149
	v_fma_f32 v133, v126, v148, -v133
	v_cvt_pk_bf16_f32 v133, v133, s0
	global_store_short v[138:139], v133, off
	v_mul_f32_e32 v133, v126, v149
	v_fmac_f32_e32 v133, v130, v148
	v_cvt_pk_bf16_f32 v133, v133, s0
	global_store_short v[138:139], v133, off offset:128
	v_or_b32_e32 v138, 3, v132
	v_ashrrev_i32_e32 v139, 31, v138
	v_lshlrev_b64 v[138:139], 8, v[138:139]
	v_lshl_add_u64 v[138:139], s[52:53], 0, v[138:139]
	v_lshl_add_u64 v[142:143], v[138:139], 0, s[56:57]
	v_lshl_add_u64 v[142:143], v[142:143], 0, v[2:3]
	v_lshl_add_u64 v[138:139], v[138:139], 0, vcc
	v_lshl_add_u64 v[138:139], v[138:139], 0, v[2:3]
	v_mul_f32_e32 v133, v123, v151
	v_fma_f32 v133, v119, v150, -v133
	v_cvt_pk_bf16_f32 v133, v133, s0
	global_store_short v[142:143], v133, off
	v_mul_f32_e32 v133, v119, v151
	v_fmac_f32_e32 v133, v123, v150
	v_cvt_pk_bf16_f32 v133, v133, s0
	global_store_short v[142:143], v133, off offset:128
	v_mul_f32_e32 v133, v131, v151
	v_fma_f32 v133, v127, v150, -v133
	v_cvt_pk_bf16_f32 v133, v133, s0
	global_store_short v[138:139], v133, off
	v_mul_f32_e32 v133, v127, v151
	v_fmac_f32_e32 v133, v131, v150
	v_cvt_pk_bf16_f32 v133, v133, s0
	global_store_short v[138:139], v133, off offset:128
	v_or_b32_e32 v138, 16, v132
	v_ashrrev_i32_e32 v139, 31, v138
	v_lshlrev_b64 v[138:139], 8, v[138:139]
	v_lshl_add_u64 v[138:139], s[52:53], 0, v[138:139]
	v_lshl_add_u64 v[142:143], v[138:139], 0, s[56:57]
	v_lshl_add_u64 v[142:143], v[142:143], 0, v[2:3]
	v_lshl_add_u64 v[138:139], v[138:139], 0, vcc
	v_lshl_add_u64 v[138:139], v[138:139], 0, v[2:3]
	v_mul_f32_e32 v133, v104, v153
	v_fma_f32 v133, v100, v152, -v133
	v_cvt_pk_bf16_f32 v133, v133, s0
	global_store_short v[142:143], v133, off
	v_mul_f32_e32 v133, v100, v153
	v_fmac_f32_e32 v133, v104, v152
	v_cvt_pk_bf16_f32 v133, v133, s0
	global_store_short v[142:143], v133, off offset:128
	v_mul_f32_e32 v133, v112, v153
	v_fma_f32 v133, v108, v152, -v133
	v_cvt_pk_bf16_f32 v133, v133, s0
	global_store_short v[138:139], v133, off
	v_mul_f32_e32 v133, v108, v153
	v_fmac_f32_e32 v133, v112, v152
	v_cvt_pk_bf16_f32 v133, v133, s0
	global_store_short v[138:139], v133, off offset:128
	v_or_b32_e32 v138, 17, v132
	v_ashrrev_i32_e32 v139, 31, v138
	v_lshlrev_b64 v[138:139], 8, v[138:139]
	v_lshl_add_u64 v[138:139], s[52:53], 0, v[138:139]
	v_lshl_add_u64 v[142:143], v[138:139], 0, s[56:57]
	v_lshl_add_u64 v[142:143], v[142:143], 0, v[2:3]
	v_lshl_add_u64 v[138:139], v[138:139], 0, vcc
	v_lshl_add_u64 v[138:139], v[138:139], 0, v[2:3]
	v_mul_f32_e32 v133, v105, v155
	v_fma_f32 v133, v101, v154, -v133
	v_cvt_pk_bf16_f32 v133, v133, s0
	global_store_short v[142:143], v133, off
	v_mul_f32_e32 v133, v101, v155
	v_fmac_f32_e32 v133, v105, v154
	v_cvt_pk_bf16_f32 v133, v133, s0
	global_store_short v[142:143], v133, off offset:128
	v_mul_f32_e32 v133, v113, v155
	v_fma_f32 v133, v109, v154, -v133
	v_cvt_pk_bf16_f32 v133, v133, s0
; #define GAS __attribute__((address_space(1)))
; __device__ __forceinline__ bf16_t f2bf(float f) { return (bf16_t)(cvtpk(f, 0.f) & 0xffffu); }
;     __device__ __forceinline__ void operator()(const f32x4 (&acc)[2][2][4][2], int brow, int bcol, int wr, int wc, int fr, int fq) const {
;     ...
;                         const int sq = (brow & 4095) + ai * 128 + wr * 64 + m * 16 + fq * 4 + j;
;                         const float2 cs = r128[sq * 64 + i];
; #pragma unroll
;                         for (int bj = 0; bj < 2; ++bj) {
;                             const float x1 = acc[ai][bj][m][0][j], x2 = acc[ai][bj][m][1][j];
;                             GAS bf16_t* p = (GAS bf16_t*)(dst + ((size_t)(b * 8 + vh0 + bj) * S + sq) * 128);
;                             p[i] = f2bf(x1 * cs.x - x2 * cs.y); p[64 + i] = f2bf(x2 * cs.x + x1 * cs.y);
	global_store_short v[138:139], v133, off
	v_mul_f32_e32 v133, v109, v155
	v_fmac_f32_e32 v133, v113, v154
	v_cvt_pk_bf16_f32 v133, v133, s0
	global_store_short v[138:139], v133, off offset:128
	v_or_b32_e32 v138, 18, v132
	v_ashrrev_i32_e32 v139, 31, v138
	v_lshlrev_b64 v[138:139], 8, v[138:139]
	v_lshl_add_u64 v[138:139], s[52:53], 0, v[138:139]
	v_lshl_add_u64 v[142:143], v[138:139], 0, s[56:57]
	v_lshl_add_u64 v[142:143], v[142:143], 0, v[2:3]
	v_lshl_add_u64 v[138:139], v[138:139], 0, vcc
	v_lshl_add_u64 v[138:139], v[138:139], 0, v[2:3]
	v_mul_f32_e32 v133, v106, v157
	v_fma_f32 v133, v102, v156, -v133
	v_cvt_pk_bf16_f32 v133, v133, s0
	global_store_short v[142:143], v133, off
	v_mul_f32_e32 v133, v102, v157
	v_fmac_f32_e32 v133, v106, v156
	v_cvt_pk_bf16_f32 v133, v133, s0
	global_store_short v[142:143], v133, off offset:128
	v_mul_f32_e32 v133, v114, v157
	v_fma_f32 v133, v110, v156, -v133
	v_cvt_pk_bf16_f32 v133, v133, s0
	global_store_short v[138:139], v133, off
	v_mul_f32_e32 v133, v110, v157
	v_fmac_f32_e32 v133, v114, v156
	v_cvt_pk_bf16_f32 v133, v133, s0
	global_store_short v[138:139], v133, off offset:128
	v_or_b32_e32 v138, 19, v132
	v_ashrrev_i32_e32 v139, 31, v138
	v_lshlrev_b64 v[138:139], 8, v[138:139]
	v_lshl_add_u64 v[138:139], s[52:53], 0, v[138:139]
	v_lshl_add_u64 v[142:143], v[138:139], 0, s[56:57]
	v_lshl_add_u64 v[142:143], v[142:143], 0, v[2:3]
	v_lshl_add_u64 v[138:139], v[138:139], 0, vcc
	v_lshl_add_u64 v[138:139], v[138:139], 0, v[2:3]
	v_mul_f32_e32 v133, v107, v159
	v_fma_f32 v133, v103, v158, -v133
	v_cvt_pk_bf16_f32 v133, v133, s0
	global_store_short v[142:143], v133, off
	v_mul_f32_e32 v133, v103, v159
	v_fmac_f32_e32 v133, v107, v158
	v_cvt_pk_bf16_f32 v133, v133, s0
	global_store_short v[142:143], v133, off offset:128
	v_mul_f32_e32 v133, v115, v159
	v_fma_f32 v133, v111, v158, -v133
	v_cvt_pk_bf16_f32 v133, v133, s0
	global_store_short v[138:139], v133, off
	v_mul_f32_e32 v133, v111, v159
	v_fmac_f32_e32 v133, v115, v158
	v_cvt_pk_bf16_f32 v133, v133, s0
	global_store_short v[138:139], v133, off offset:128
	v_or_b32_e32 v138, 32, v132
	v_ashrrev_i32_e32 v139, 31, v138
	v_lshlrev_b64 v[138:139], 8, v[138:139]
	v_lshl_add_u64 v[138:139], s[52:53], 0, v[138:139]
	v_lshl_add_u64 v[142:143], v[138:139], 0, s[56:57]
	v_lshl_add_u64 v[142:143], v[142:143], 0, v[2:3]
	v_lshl_add_u64 v[138:139], v[138:139], 0, vcc
	v_lshl_add_u64 v[138:139], v[138:139], 0, v[2:3]
	v_mul_f32_e32 v133, v88, v161
	v_fma_f32 v133, v84, v160, -v133
	v_cvt_pk_bf16_f32 v133, v133, s0
	global_store_short v[142:143], v133, off
	v_mul_f32_e32 v133, v84, v161
	v_fmac_f32_e32 v133, v88, v160
	v_cvt_pk_bf16_f32 v133, v133, s0
	global_store_short v[142:143], v133, off offset:128
	v_mul_f32_e32 v133, v96, v161
	v_fma_f32 v133, v92, v160, -v133
	v_cvt_pk_bf16_f32 v133, v133, s0
	global_store_short v[138:139], v133, off
	v_mul_f32_e32 v133, v92, v161
	v_fmac_f32_e32 v133, v96, v160
	v_cvt_pk_bf16_f32 v133, v133, s0
	global_store_short v[138:139], v133, off offset:128
	v_or_b32_e32 v138, 33, v132
	v_ashrrev_i32_e32 v139, 31, v138
	v_lshlrev_b64 v[138:139], 8, v[138:139]
	v_lshl_add_u64 v[138:139], s[52:53], 0, v[138:139]
	v_lshl_add_u64 v[142:143], v[138:139], 0, s[56:57]
	v_lshl_add_u64 v[142:143], v[142:143], 0, v[2:3]
	v_lshl_add_u64 v[138:139], v[138:139], 0, vcc
	v_lshl_add_u64 v[138:139], v[138:139], 0, v[2:3]
	v_mul_f32_e32 v133, v89, v163
	v_fma_f32 v133, v85, v162, -v133
	v_cvt_pk_bf16_f32 v133, v133, s0
	global_store_short v[142:143], v133, off
	v_mul_f32_e32 v133, v85, v163
	v_fmac_f32_e32 v133, v89, v162
	v_cvt_pk_bf16_f32 v133, v133, s0
	global_store_short v[142:143], v133, off offset:128
	v_mul_f32_e32 v133, v97, v163
	v_fma_f32 v133, v93, v162, -v133
	v_cvt_pk_bf16_f32 v133, v133, s0
	global_store_short v[138:139], v133, off
	v_mul_f32_e32 v133, v93, v163
	v_fmac_f32_e32 v133, v97, v162
	v_cvt_pk_bf16_f32 v133, v133, s0
	global_store_short v[138:139], v133, off offset:128
	v_or_b32_e32 v138, 34, v132
	v_ashrrev_i32_e32 v139, 31, v138
	v_lshlrev_b64 v[138:139], 8, v[138:139]
	v_lshl_add_u64 v[138:139], s[52:53], 0, v[138:139]
	v_lshl_add_u64 v[142:143], v[138:139], 0, s[56:57]
	v_lshl_add_u64 v[142:143], v[142:143], 0, v[2:3]
	v_lshl_add_u64 v[138:139], v[138:139], 0, vcc
	v_lshl_add_u64 v[138:139], v[138:139], 0, v[2:3]
	v_mul_f32_e32 v133, v90, v165
	v_fma_f32 v133, v86, v164, -v133
	v_cvt_pk_bf16_f32 v133, v133, s0
	global_store_short v[142:143], v133, off
	v_mul_f32_e32 v133, v86, v165
	v_fmac_f32_e32 v133, v90, v164
	v_cvt_pk_bf16_f32 v133, v133, s0
	global_store_short v[142:143], v133, off offset:128
	v_mul_f32_e32 v133, v98, v165
	v_fma_f32 v133, v94, v164, -v133
	v_cvt_pk_bf16_f32 v133, v133, s0
	global_store_short v[138:139], v133, off
	v_mul_f32_e32 v133, v94, v165
	v_fmac_f32_e32 v133, v98, v164
	v_cvt_pk_bf16_f32 v133, v133, s0
	global_store_short v[138:139], v133, off offset:128
	v_or_b32_e32 v138, 35, v132
	v_ashrrev_i32_e32 v139, 31, v138
	v_lshlrev_b64 v[138:139], 8, v[138:139]
	v_lshl_add_u64 v[138:139], s[52:53], 0, v[138:139]
	v_lshl_add_u64 v[142:143], v[138:139], 0, s[56:57]
	v_lshl_add_u64 v[142:143], v[142:143], 0, v[2:3]
	v_lshl_add_u64 v[138:139], v[138:139], 0, vcc
	v_lshl_add_u64 v[138:139], v[138:139], 0, v[2:3]
	v_mul_f32_e32 v133, v91, v167
	v_fma_f32 v133, v87, v166, -v133
	v_cvt_pk_bf16_f32 v133, v133, s0
	global_store_short v[142:143], v133, off
	v_mul_f32_e32 v133, v87, v167
	v_fmac_f32_e32 v133, v91, v166
	v_cvt_pk_bf16_f32 v133, v133, s0
	global_store_short v[142:143], v133, off offset:128
	v_mul_f32_e32 v133, v99, v167
	v_fma_f32 v133, v95, v166, -v133
	v_cvt_pk_bf16_f32 v133, v133, s0
; #define GAS __attribute__((address_space(1)))
; __device__ __forceinline__ bf16_t f2bf(float f) { return (bf16_t)(cvtpk(f, 0.f) & 0xffffu); }
;     __device__ __forceinline__ void operator()(const f32x4 (&acc)[2][2][4][2], int brow, int bcol, int wr, int wc, int fr, int fq) const {
;     ...
;                         const int sq = (brow & 4095) + ai * 128 + wr * 64 + m * 16 + fq * 4 + j;
;                         const float2 cs = r128[sq * 64 + i];
; #pragma unroll
;                         for (int bj = 0; bj < 2; ++bj) {
;                             const float x1 = acc[ai][bj][m][0][j], x2 = acc[ai][bj][m][1][j];
;                             GAS bf16_t* p = (GAS bf16_t*)(dst + ((size_t)(b * 8 + vh0 + bj) * S + sq) * 128);
;                             p[i] = f2bf(x1 * cs.x - x2 * cs.y); p[64 + i] = f2bf(x2 * cs.x + x1 * cs.y);
	global_store_short v[138:139], v133, off
	v_mul_f32_e32 v133, v95, v167
	v_fmac_f32_e32 v133, v99, v166
	v_cvt_pk_bf16_f32 v133, v133, s0
	global_store_short v[138:139], v133, off offset:128
	v_or_b32_e32 v138, 48, v132
	v_ashrrev_i32_e32 v139, 31, v138
	v_lshlrev_b64 v[138:139], 8, v[138:139]
	v_lshl_add_u64 v[138:139], s[52:53], 0, v[138:139]
	v_lshl_add_u64 v[142:143], v[138:139], 0, s[56:57]
	v_lshl_add_u64 v[142:143], v[142:143], 0, v[2:3]
	v_lshl_add_u64 v[138:139], v[138:139], 0, vcc
	v_lshl_add_u64 v[138:139], v[138:139], 0, v[2:3]
	v_mul_f32_e32 v133, v72, v169
	v_fma_f32 v133, v68, v168, -v133
	v_cvt_pk_bf16_f32 v133, v133, s0
	global_store_short v[142:143], v133, off
	v_mul_f32_e32 v133, v68, v169
	v_fmac_f32_e32 v133, v72, v168
	v_cvt_pk_bf16_f32 v133, v133, s0
	global_store_short v[142:143], v133, off offset:128
	v_mul_f32_e32 v133, v80, v169
	v_fma_f32 v133, v76, v168, -v133
	v_cvt_pk_bf16_f32 v133, v133, s0
	global_store_short v[138:139], v133, off
	v_mul_f32_e32 v133, v76, v169
	v_fmac_f32_e32 v133, v80, v168
	v_cvt_pk_bf16_f32 v133, v133, s0
	global_store_short v[138:139], v133, off offset:128
	v_or_b32_e32 v138, 49, v132
	v_ashrrev_i32_e32 v139, 31, v138
	v_lshlrev_b64 v[138:139], 8, v[138:139]
	v_lshl_add_u64 v[138:139], s[52:53], 0, v[138:139]
	v_lshl_add_u64 v[142:143], v[138:139], 0, s[56:57]
	v_lshl_add_u64 v[142:143], v[142:143], 0, v[2:3]
	v_lshl_add_u64 v[138:139], v[138:139], 0, vcc
	v_lshl_add_u64 v[138:139], v[138:139], 0, v[2:3]
	v_mul_f32_e32 v133, v73, v171
	v_fma_f32 v133, v69, v170, -v133
	v_cvt_pk_bf16_f32 v133, v133, s0
	global_store_short v[142:143], v133, off
	v_mul_f32_e32 v133, v69, v171
	v_fmac_f32_e32 v133, v73, v170
	v_cvt_pk_bf16_f32 v133, v133, s0
	global_store_short v[142:143], v133, off offset:128
	v_mul_f32_e32 v133, v81, v171
	v_fma_f32 v133, v77, v170, -v133
	v_cvt_pk_bf16_f32 v133, v133, s0
	global_store_short v[138:139], v133, off
	v_mul_f32_e32 v133, v77, v171
	v_fmac_f32_e32 v133, v81, v170
	v_cvt_pk_bf16_f32 v133, v133, s0
	global_store_short v[138:139], v133, off offset:128
	v_or_b32_e32 v138, 50, v132
	v_ashrrev_i32_e32 v139, 31, v138
	v_lshlrev_b64 v[138:139], 8, v[138:139]
	v_lshl_add_u64 v[138:139], s[52:53], 0, v[138:139]
	v_lshl_add_u64 v[142:143], v[138:139], 0, s[56:57]
	v_lshl_add_u64 v[142:143], v[142:143], 0, v[2:3]
	v_lshl_add_u64 v[138:139], v[138:139], 0, vcc
	v_lshl_add_u64 v[138:139], v[138:139], 0, v[2:3]
	v_mul_f32_e32 v133, v74, v173
	v_fma_f32 v133, v70, v172, -v133
	v_cvt_pk_bf16_f32 v133, v133, s0
	global_store_short v[142:143], v133, off
	v_mul_f32_e32 v133, v70, v173
	v_fmac_f32_e32 v133, v74, v172
	v_cvt_pk_bf16_f32 v133, v133, s0
	global_store_short v[142:143], v133, off offset:128
	v_mul_f32_e32 v133, v82, v173
	v_fma_f32 v133, v78, v172, -v133
	v_cvt_pk_bf16_f32 v133, v133, s0
	global_store_short v[138:139], v133, off
	v_mul_f32_e32 v133, v78, v173
	v_fmac_f32_e32 v133, v82, v172
	v_cvt_pk_bf16_f32 v133, v133, s0
	global_store_short v[138:139], v133, off offset:128
	v_or_b32_e32 v138, 51, v132
	v_ashrrev_i32_e32 v139, 31, v138
	v_lshlrev_b64 v[138:139], 8, v[138:139]
	v_lshl_add_u64 v[138:139], s[52:53], 0, v[138:139]
	v_lshl_add_u64 v[142:143], v[138:139], 0, s[56:57]
	v_lshl_add_u64 v[142:143], v[142:143], 0, v[2:3]
	v_lshl_add_u64 v[138:139], v[138:139], 0, vcc
	v_lshl_add_u64 v[138:139], v[138:139], 0, v[2:3]
	v_mul_f32_e32 v133, v75, v175
	v_fma_f32 v133, v71, v174, -v133
	v_cvt_pk_bf16_f32 v133, v133, s0
	global_store_short v[142:143], v133, off
	v_mul_f32_e32 v133, v71, v175
	v_fmac_f32_e32 v133, v75, v174
	v_cvt_pk_bf16_f32 v133, v133, s0
	global_store_short v[142:143], v133, off offset:128
	v_mul_f32_e32 v133, v83, v175
	v_fma_f32 v133, v79, v174, -v133
	v_cvt_pk_bf16_f32 v133, v133, s0
	global_store_short v[138:139], v133, off
	v_mul_f32_e32 v133, v79, v175
	v_fmac_f32_e32 v133, v83, v174
	v_cvt_pk_bf16_f32 v133, v133, s0
	global_store_short v[138:139], v133, off offset:128
	v_add_u32_e32 v138, 0x80, v132
	v_ashrrev_i32_e32 v139, 31, v138
	v_lshlrev_b64 v[138:139], 8, v[138:139]
	v_lshl_add_u64 v[138:139], s[52:53], 0, v[138:139]
	v_lshl_add_u64 v[142:143], v[138:139], 0, s[56:57]
	v_lshl_add_u64 v[142:143], v[142:143], 0, v[2:3]
	v_lshl_add_u64 v[138:139], v[138:139], 0, vcc
	v_lshl_add_u64 v[138:139], v[138:139], 0, v[2:3]
	v_mul_f32_e32 v133, v56, v177
	v_fma_f32 v133, v52, v176, -v133
	v_cvt_pk_bf16_f32 v133, v133, s0
	global_store_short v[142:143], v133, off
	v_mul_f32_e32 v133, v52, v177
	v_fmac_f32_e32 v133, v56, v176
	v_cvt_pk_bf16_f32 v133, v133, s0
	global_store_short v[142:143], v133, off offset:128
	v_mul_f32_e32 v133, v64, v177
	v_fma_f32 v133, v60, v176, -v133
	v_cvt_pk_bf16_f32 v133, v133, s0
	global_store_short v[138:139], v133, off
	v_mul_f32_e32 v133, v60, v177
	v_fmac_f32_e32 v133, v64, v176
	v_cvt_pk_bf16_f32 v133, v133, s0
	global_store_short v[138:139], v133, off offset:128
	v_add_u32_e32 v138, 0x81, v132
	v_ashrrev_i32_e32 v139, 31, v138
	v_lshlrev_b64 v[138:139], 8, v[138:139]
	v_lshl_add_u64 v[138:139], s[52:53], 0, v[138:139]
	v_lshl_add_u64 v[142:143], v[138:139], 0, s[56:57]
	v_lshl_add_u64 v[142:143], v[142:143], 0, v[2:3]
	v_lshl_add_u64 v[138:139], v[138:139], 0, vcc
	v_lshl_add_u64 v[138:139], v[138:139], 0, v[2:3]
	v_mul_f32_e32 v133, v57, v179
	v_fma_f32 v133, v53, v178, -v133
	v_cvt_pk_bf16_f32 v133, v133, s0
	global_store_short v[142:143], v133, off
	v_mul_f32_e32 v133, v53, v179
	v_fmac_f32_e32 v133, v57, v178
	v_cvt_pk_bf16_f32 v133, v133, s0
	global_store_short v[142:143], v133, off offset:128
	v_mul_f32_e32 v133, v65, v179
	v_fma_f32 v133, v61, v178, -v133
	v_cvt_pk_bf16_f32 v133, v133, s0
; #define GAS __attribute__((address_space(1)))
; __device__ __forceinline__ bf16_t f2bf(float f) { return (bf16_t)(cvtpk(f, 0.f) & 0xffffu); }
;     __device__ __forceinline__ void operator()(const f32x4 (&acc)[2][2][4][2], int brow, int bcol, int wr, int wc, int fr, int fq) const {
;     ...
;                         const int sq = (brow & 4095) + ai * 128 + wr * 64 + m * 16 + fq * 4 + j;
;                         const float2 cs = r128[sq * 64 + i];
; #pragma unroll
;                         for (int bj = 0; bj < 2; ++bj) {
;                             const float x1 = acc[ai][bj][m][0][j], x2 = acc[ai][bj][m][1][j];
;                             GAS bf16_t* p = (GAS bf16_t*)(dst + ((size_t)(b * 8 + vh0 + bj) * S + sq) * 128);
;                             p[i] = f2bf(x1 * cs.x - x2 * cs.y); p[64 + i] = f2bf(x2 * cs.x + x1 * cs.y);
	global_store_short v[138:139], v133, off
	v_mul_f32_e32 v133, v61, v179
	v_fmac_f32_e32 v133, v65, v178
	v_cvt_pk_bf16_f32 v133, v133, s0
	global_store_short v[138:139], v133, off offset:128
	v_add_u32_e32 v138, 0x82, v132
	v_ashrrev_i32_e32 v139, 31, v138
	v_lshlrev_b64 v[138:139], 8, v[138:139]
	v_lshl_add_u64 v[138:139], s[52:53], 0, v[138:139]
	v_lshl_add_u64 v[142:143], v[138:139], 0, s[56:57]
	v_lshl_add_u64 v[142:143], v[142:143], 0, v[2:3]
	v_lshl_add_u64 v[138:139], v[138:139], 0, vcc
	v_lshl_add_u64 v[138:139], v[138:139], 0, v[2:3]
	v_mul_f32_e32 v133, v58, v181
	v_fma_f32 v133, v54, v180, -v133
	v_cvt_pk_bf16_f32 v133, v133, s0
	global_store_short v[142:143], v133, off
	v_mul_f32_e32 v133, v54, v181
	v_fmac_f32_e32 v133, v58, v180
	v_cvt_pk_bf16_f32 v133, v133, s0
	global_store_short v[142:143], v133, off offset:128
	v_mul_f32_e32 v133, v66, v181
	v_fma_f32 v133, v62, v180, -v133
	v_cvt_pk_bf16_f32 v133, v133, s0
	global_store_short v[138:139], v133, off
	v_mul_f32_e32 v133, v62, v181
	v_fmac_f32_e32 v133, v66, v180
	v_cvt_pk_bf16_f32 v133, v133, s0
	global_store_short v[138:139], v133, off offset:128
	v_add_u32_e32 v138, 0x83, v132
	v_ashrrev_i32_e32 v139, 31, v138
	v_lshlrev_b64 v[138:139], 8, v[138:139]
	v_lshl_add_u64 v[138:139], s[52:53], 0, v[138:139]
	v_lshl_add_u64 v[142:143], v[138:139], 0, s[56:57]
	v_lshl_add_u64 v[142:143], v[142:143], 0, v[2:3]
	v_lshl_add_u64 v[138:139], v[138:139], 0, vcc
	v_lshl_add_u64 v[138:139], v[138:139], 0, v[2:3]
	v_mul_f32_e32 v133, v59, v183
	v_fma_f32 v133, v55, v182, -v133
	v_cvt_pk_bf16_f32 v133, v133, s0
	global_store_short v[142:143], v133, off
	v_mul_f32_e32 v133, v55, v183
	v_fmac_f32_e32 v133, v59, v182
	v_cvt_pk_bf16_f32 v133, v133, s0
	global_store_short v[142:143], v133, off offset:128
	v_mul_f32_e32 v133, v67, v183
	v_fma_f32 v133, v63, v182, -v133
	v_cvt_pk_bf16_f32 v133, v133, s0
	global_store_short v[138:139], v133, off
	v_mul_f32_e32 v133, v63, v183
	v_fmac_f32_e32 v133, v67, v182
	v_cvt_pk_bf16_f32 v133, v133, s0
	global_store_short v[138:139], v133, off offset:128
	v_add_u32_e32 v138, 0x90, v132
	v_ashrrev_i32_e32 v139, 31, v138
	v_lshlrev_b64 v[138:139], 8, v[138:139]
	v_lshl_add_u64 v[138:139], s[52:53], 0, v[138:139]
	v_lshl_add_u64 v[142:143], v[138:139], 0, s[56:57]
	v_lshl_add_u64 v[142:143], v[142:143], 0, v[2:3]
	v_lshl_add_u64 v[138:139], v[138:139], 0, vcc
	v_lshl_add_u64 v[138:139], v[138:139], 0, v[2:3]
	v_mul_f32_e32 v133, v40, v185
	v_fma_f32 v133, v36, v184, -v133
	v_cvt_pk_bf16_f32 v133, v133, s0
	global_store_short v[142:143], v133, off
	v_mul_f32_e32 v133, v36, v185
	v_fmac_f32_e32 v133, v40, v184
	v_cvt_pk_bf16_f32 v133, v133, s0
	global_store_short v[142:143], v133, off offset:128
	v_mul_f32_e32 v133, v48, v185
	v_fma_f32 v133, v44, v184, -v133
	v_cvt_pk_bf16_f32 v133, v133, s0
	global_store_short v[138:139], v133, off
	v_mul_f32_e32 v133, v44, v185
	v_fmac_f32_e32 v133, v48, v184
	v_cvt_pk_bf16_f32 v133, v133, s0
	global_store_short v[138:139], v133, off offset:128
	v_add_u32_e32 v138, 0x91, v132
	v_ashrrev_i32_e32 v139, 31, v138
	v_lshlrev_b64 v[138:139], 8, v[138:139]
	v_lshl_add_u64 v[138:139], s[52:53], 0, v[138:139]
	v_lshl_add_u64 v[142:143], v[138:139], 0, s[56:57]
	v_lshl_add_u64 v[142:143], v[142:143], 0, v[2:3]
	v_lshl_add_u64 v[138:139], v[138:139], 0, vcc
	v_lshl_add_u64 v[138:139], v[138:139], 0, v[2:3]
	v_mul_f32_e32 v133, v41, v187
	v_fma_f32 v133, v37, v186, -v133
	v_cvt_pk_bf16_f32 v133, v133, s0
	global_store_short v[142:143], v133, off
	v_mul_f32_e32 v133, v37, v187
	v_fmac_f32_e32 v133, v41, v186
	v_cvt_pk_bf16_f32 v133, v133, s0
	global_store_short v[142:143], v133, off offset:128
	v_mul_f32_e32 v133, v49, v187
	v_fma_f32 v133, v45, v186, -v133
	v_cvt_pk_bf16_f32 v133, v133, s0
	global_store_short v[138:139], v133, off
	v_mul_f32_e32 v133, v45, v187
	v_fmac_f32_e32 v133, v49, v186
	v_cvt_pk_bf16_f32 v133, v133, s0
	global_store_short v[138:139], v133, off offset:128
	v_add_u32_e32 v138, 0x92, v132
	v_ashrrev_i32_e32 v139, 31, v138
	v_lshlrev_b64 v[138:139], 8, v[138:139]
	v_lshl_add_u64 v[138:139], s[52:53], 0, v[138:139]
	v_lshl_add_u64 v[142:143], v[138:139], 0, s[56:57]
	v_lshl_add_u64 v[142:143], v[142:143], 0, v[2:3]
	v_lshl_add_u64 v[138:139], v[138:139], 0, vcc
	v_lshl_add_u64 v[138:139], v[138:139], 0, v[2:3]
	v_mul_f32_e32 v133, v42, v189
	v_fma_f32 v133, v38, v188, -v133
	v_cvt_pk_bf16_f32 v133, v133, s0
	global_store_short v[142:143], v133, off
	v_mul_f32_e32 v133, v38, v189
	v_fmac_f32_e32 v133, v42, v188
	v_cvt_pk_bf16_f32 v133, v133, s0
	global_store_short v[142:143], v133, off offset:128
	v_mul_f32_e32 v133, v50, v189
	v_fma_f32 v133, v46, v188, -v133
	v_cvt_pk_bf16_f32 v133, v133, s0
	global_store_short v[138:139], v133, off
	v_mul_f32_e32 v133, v46, v189
	v_fmac_f32_e32 v133, v50, v188
	v_cvt_pk_bf16_f32 v133, v133, s0
	global_store_short v[138:139], v133, off offset:128
	v_add_u32_e32 v138, 0x93, v132
	v_ashrrev_i32_e32 v139, 31, v138
	v_lshlrev_b64 v[138:139], 8, v[138:139]
	v_lshl_add_u64 v[138:139], s[52:53], 0, v[138:139]
	v_lshl_add_u64 v[142:143], v[138:139], 0, s[56:57]
	v_lshl_add_u64 v[142:143], v[142:143], 0, v[2:3]
	v_lshl_add_u64 v[138:139], v[138:139], 0, vcc
	v_lshl_add_u64 v[138:139], v[138:139], 0, v[2:3]
	v_mul_f32_e32 v133, v43, v191
	v_fma_f32 v133, v39, v190, -v133
	v_cvt_pk_bf16_f32 v133, v133, s0
	global_store_short v[142:143], v133, off
	v_mul_f32_e32 v133, v39, v191
	v_fmac_f32_e32 v133, v43, v190
	v_cvt_pk_bf16_f32 v133, v133, s0
	global_store_short v[142:143], v133, off offset:128
	v_mul_f32_e32 v133, v51, v191
	v_fma_f32 v133, v47, v190, -v133
	v_cvt_pk_bf16_f32 v133, v133, s0
; #define GAS __attribute__((address_space(1)))
; __device__ __forceinline__ bf16_t f2bf(float f) { return (bf16_t)(cvtpk(f, 0.f) & 0xffffu); }
;     __device__ __forceinline__ void operator()(const f32x4 (&acc)[2][2][4][2], int brow, int bcol, int wr, int wc, int fr, int fq) const {
;     ...
;                         const int sq = (brow & 4095) + ai * 128 + wr * 64 + m * 16 + fq * 4 + j;
;                         const float2 cs = r128[sq * 64 + i];
; #pragma unroll
;                         for (int bj = 0; bj < 2; ++bj) {
;                             const float x1 = acc[ai][bj][m][0][j], x2 = acc[ai][bj][m][1][j];
;                             GAS bf16_t* p = (GAS bf16_t*)(dst + ((size_t)(b * 8 + vh0 + bj) * S + sq) * 128);
;                             p[i] = f2bf(x1 * cs.x - x2 * cs.y); p[64 + i] = f2bf(x2 * cs.x + x1 * cs.y);
	global_store_short v[138:139], v133, off
	v_mul_f32_e32 v133, v47, v191
	v_fmac_f32_e32 v133, v51, v190
	v_cvt_pk_bf16_f32 v133, v133, s0
	global_store_short v[138:139], v133, off offset:128
	v_add_u32_e32 v138, 0xa0, v132
	v_ashrrev_i32_e32 v139, 31, v138
	v_lshlrev_b64 v[138:139], 8, v[138:139]
	v_lshl_add_u64 v[138:139], s[52:53], 0, v[138:139]
	v_lshl_add_u64 v[142:143], v[138:139], 0, s[56:57]
	v_lshl_add_u64 v[142:143], v[142:143], 0, v[2:3]
	v_lshl_add_u64 v[138:139], v[138:139], 0, vcc
	v_lshl_add_u64 v[138:139], v[138:139], 0, v[2:3]
	v_mul_f32_e32 v133, v24, v193
	v_fma_f32 v133, v20, v192, -v133
	v_cvt_pk_bf16_f32 v133, v133, s0
	global_store_short v[142:143], v133, off
	v_mul_f32_e32 v133, v20, v193
	v_fmac_f32_e32 v133, v24, v192
	v_cvt_pk_bf16_f32 v133, v133, s0
	global_store_short v[142:143], v133, off offset:128
	v_mul_f32_e32 v133, v32, v193
	v_fma_f32 v133, v28, v192, -v133
	v_cvt_pk_bf16_f32 v133, v133, s0
	global_store_short v[138:139], v133, off
	v_mul_f32_e32 v133, v28, v193
	v_fmac_f32_e32 v133, v32, v192
	v_cvt_pk_bf16_f32 v133, v133, s0
	global_store_short v[138:139], v133, off offset:128
	v_add_u32_e32 v138, 0xa1, v132
	v_ashrrev_i32_e32 v139, 31, v138
	v_lshlrev_b64 v[138:139], 8, v[138:139]
	v_lshl_add_u64 v[138:139], s[52:53], 0, v[138:139]
	v_lshl_add_u64 v[142:143], v[138:139], 0, s[56:57]
	v_lshl_add_u64 v[142:143], v[142:143], 0, v[2:3]
	v_lshl_add_u64 v[138:139], v[138:139], 0, vcc
	v_lshl_add_u64 v[138:139], v[138:139], 0, v[2:3]
	v_mul_f32_e32 v133, v25, v195
	v_fma_f32 v133, v21, v194, -v133
	v_cvt_pk_bf16_f32 v133, v133, s0
	global_store_short v[142:143], v133, off
	v_mul_f32_e32 v133, v21, v195
	v_fmac_f32_e32 v133, v25, v194
	v_cvt_pk_bf16_f32 v133, v133, s0
	global_store_short v[142:143], v133, off offset:128
	v_mul_f32_e32 v133, v33, v195
	v_fma_f32 v133, v29, v194, -v133
	v_cvt_pk_bf16_f32 v133, v133, s0
	global_store_short v[138:139], v133, off
	v_mul_f32_e32 v133, v29, v195
	v_fmac_f32_e32 v133, v33, v194
	v_cvt_pk_bf16_f32 v133, v133, s0
	global_store_short v[138:139], v133, off offset:128
	v_add_u32_e32 v138, 0xa2, v132
	v_ashrrev_i32_e32 v139, 31, v138
	v_lshlrev_b64 v[138:139], 8, v[138:139]
	v_lshl_add_u64 v[138:139], s[52:53], 0, v[138:139]
	v_lshl_add_u64 v[142:143], v[138:139], 0, s[56:57]
	v_lshl_add_u64 v[142:143], v[142:143], 0, v[2:3]
	v_lshl_add_u64 v[138:139], v[138:139], 0, vcc
	v_lshl_add_u64 v[138:139], v[138:139], 0, v[2:3]
	v_mul_f32_e32 v133, v26, v197
	v_fma_f32 v133, v22, v196, -v133
	v_cvt_pk_bf16_f32 v133, v133, s0
	global_store_short v[142:143], v133, off
	v_mul_f32_e32 v133, v22, v197
	v_fmac_f32_e32 v133, v26, v196
	v_cvt_pk_bf16_f32 v133, v133, s0
	global_store_short v[142:143], v133, off offset:128
	v_mul_f32_e32 v133, v34, v197
	v_fma_f32 v133, v30, v196, -v133
	v_cvt_pk_bf16_f32 v133, v133, s0
	global_store_short v[138:139], v133, off
	v_mul_f32_e32 v133, v30, v197
	v_fmac_f32_e32 v133, v34, v196
	v_cvt_pk_bf16_f32 v133, v133, s0
	global_store_short v[138:139], v133, off offset:128
	v_add_u32_e32 v138, 0xa3, v132
	v_ashrrev_i32_e32 v139, 31, v138
	v_lshlrev_b64 v[138:139], 8, v[138:139]
	v_lshl_add_u64 v[138:139], s[52:53], 0, v[138:139]
	v_lshl_add_u64 v[142:143], v[138:139], 0, s[56:57]
	v_lshl_add_u64 v[142:143], v[142:143], 0, v[2:3]
	v_lshl_add_u64 v[138:139], v[138:139], 0, vcc
	v_lshl_add_u64 v[138:139], v[138:139], 0, v[2:3]
	v_mul_f32_e32 v133, v27, v209
	v_fma_f32 v133, v23, v208, -v133
	v_cvt_pk_bf16_f32 v133, v133, s0
	global_store_short v[142:143], v133, off
	v_mul_f32_e32 v133, v23, v209
	v_fmac_f32_e32 v133, v27, v208
	v_cvt_pk_bf16_f32 v133, v133, s0
	global_store_short v[142:143], v133, off offset:128
	v_mul_f32_e32 v133, v35, v209
	v_fma_f32 v133, v31, v208, -v133
	v_cvt_pk_bf16_f32 v133, v133, s0
	global_store_short v[138:139], v133, off
	v_mul_f32_e32 v133, v31, v209
; #define GAS __attribute__((address_space(1)))
; __device__ __forceinline__ bf16_t f2bf(float f) { return (bf16_t)(cvtpk(f, 0.f) & 0xffffu); }
;     __device__ __forceinline__ void operator()(const f32x4 (&acc)[2][2][4][2], int brow, int bcol, int wr, int wc, int fr, int fq) const {
;     ...
;                         const int sq = (brow & 4095) + ai * 128 + wr * 64 + m * 16 + fq * 4 + j;
;                         const float2 cs = r128[sq * 64 + i];
; #pragma unroll
;                         for (int bj = 0; bj < 2; ++bj) {
;                             const float x1 = acc[ai][bj][m][0][j], x2 = acc[ai][bj][m][1][j];
;                             GAS bf16_t* p = (GAS bf16_t*)(dst + ((size_t)(b * 8 + vh0 + bj) * S + sq) * 128);
;                             p[i] = f2bf(x1 * cs.x - x2 * cs.y); p[64 + i] = f2bf(x2 * cs.x + x1 * cs.y);
	v_fmac_f32_e32 v133, v35, v208
	v_cvt_pk_bf16_f32 v133, v133, s0
	global_store_short v[138:139], v133, off offset:128
	v_add_u32_e32 v138, 0xb0, v132
	v_ashrrev_i32_e32 v139, 31, v138
	v_lshlrev_b64 v[138:139], 8, v[138:139]
	v_lshl_add_u64 v[138:139], s[52:53], 0, v[138:139]
	v_lshl_add_u64 v[142:143], v[138:139], 0, s[56:57]
	v_lshl_add_u64 v[142:143], v[142:143], 0, v[2:3]
	v_lshl_add_u64 v[138:139], v[138:139], 0, vcc
	v_lshl_add_u64 v[138:139], v[138:139], 0, v[2:3]
	v_mul_f32_e32 v133, v8, v211
	v_fma_f32 v133, v4, v210, -v133
	v_cvt_pk_bf16_f32 v133, v133, s0
	global_store_short v[142:143], v133, off
	v_mul_f32_e32 v133, v4, v211
	v_fmac_f32_e32 v133, v8, v210
	v_cvt_pk_bf16_f32 v133, v133, s0
	global_store_short v[142:143], v133, off offset:128
	v_mul_f32_e32 v133, v16, v211
	v_fma_f32 v133, v12, v210, -v133
	v_cvt_pk_bf16_f32 v133, v133, s0
	global_store_short v[138:139], v133, off
	v_mul_f32_e32 v133, v12, v211
	v_fmac_f32_e32 v133, v16, v210
	v_cvt_pk_bf16_f32 v133, v133, s0
	global_store_short v[138:139], v133, off offset:128
	v_add_u32_e32 v138, 0xb1, v132
	v_ashrrev_i32_e32 v139, 31, v138
	v_lshlrev_b64 v[138:139], 8, v[138:139]
	v_lshl_add_u64 v[138:139], s[52:53], 0, v[138:139]
	v_lshl_add_u64 v[142:143], v[138:139], 0, s[56:57]
	v_lshl_add_u64 v[142:143], v[142:143], 0, v[2:3]
	v_lshl_add_u64 v[138:139], v[138:139], 0, vcc
	v_lshl_add_u64 v[138:139], v[138:139], 0, v[2:3]
	v_mul_f32_e32 v133, v9, v213
	v_fma_f32 v133, v5, v212, -v133
	v_cvt_pk_bf16_f32 v133, v133, s0
	global_store_short v[142:143], v133, off
	v_mul_f32_e32 v133, v5, v213
	v_fmac_f32_e32 v133, v9, v212
	v_cvt_pk_bf16_f32 v133, v133, s0
	global_store_short v[142:143], v133, off offset:128
	v_mul_f32_e32 v133, v17, v213
	v_fma_f32 v133, v13, v212, -v133
	v_cvt_pk_bf16_f32 v133, v133, s0
	global_store_short v[138:139], v133, off
	v_mul_f32_e32 v133, v13, v213
	v_fmac_f32_e32 v133, v17, v212
	v_cvt_pk_bf16_f32 v133, v133, s0
	global_store_short v[138:139], v133, off offset:128
	v_add_u32_e32 v138, 0xb2, v132
	v_ashrrev_i32_e32 v139, 31, v138
	v_lshlrev_b64 v[138:139], 8, v[138:139]
	v_lshl_add_u64 v[138:139], s[52:53], 0, v[138:139]
	v_lshl_add_u64 v[142:143], v[138:139], 0, s[56:57]
	v_lshl_add_u64 v[142:143], v[142:143], 0, v[2:3]
	v_lshl_add_u64 v[138:139], v[138:139], 0, vcc
	v_lshl_add_u64 v[138:139], v[138:139], 0, v[2:3]
	v_add_u32_e32 v132, 0xb3, v132
	v_mul_f32_e32 v133, v10, v215
	v_fma_f32 v133, v6, v214, -v133
	v_cvt_pk_bf16_f32 v133, v133, s0
	global_store_short v[142:143], v133, off
	v_mul_f32_e32 v133, v6, v215
	v_fmac_f32_e32 v133, v10, v214
	v_cvt_pk_bf16_f32 v133, v133, s0
	global_store_short v[142:143], v133, off offset:128
	v_mul_f32_e32 v133, v18, v215
	v_fma_f32 v133, v14, v214, -v133
	v_cvt_pk_bf16_f32 v133, v133, s0
	global_store_short v[138:139], v133, off
	v_mul_f32_e32 v133, v14, v215
	v_fmac_f32_e32 v133, v18, v214
	v_cvt_pk_bf16_f32 v133, v133, s0
	global_store_short v[138:139], v133, off offset:128
	v_ashrrev_i32_e32 v133, 31, v132
	v_lshlrev_b64 v[132:133], 8, v[132:133]
	v_lshl_add_u64 v[132:133], s[52:53], 0, v[132:133]
	v_lshl_add_u64 v[140:141], v[132:133], 0, s[56:57]
	v_lshl_add_u64 v[140:141], v[140:141], 0, v[2:3]
	v_lshl_add_u64 v[132:133], v[132:133], 0, vcc
	v_lshl_add_u64 v[132:133], v[132:133], 0, v[2:3]
	v_mul_f32_e32 v137, v11, v217
	v_fma_f32 v137, v7, v216, -v137
	v_cvt_pk_bf16_f32 v137, v137, s0
	global_store_short v[140:141], v137, off
	v_mul_f32_e32 v137, v7, v217
	v_fmac_f32_e32 v137, v11, v216
	v_cvt_pk_bf16_f32 v137, v137, s0
	global_store_short v[140:141], v137, off offset:128
	v_mul_f32_e32 v137, v19, v217
	v_mul_f32_e32 v2, v15, v217
	v_fma_f32 v137, v15, v216, -v137
	v_fmac_f32_e32 v2, v19, v216
	v_cvt_pk_bf16_f32 v137, v137, s0
	v_cvt_pk_bf16_f32 v2, v2, s0
	global_store_short v[132:133], v137, off
	global_store_short v[132:133], v2, off offset:128
